# attention PV: V fragment refill reads issued right behind the MFMA that consumed the quad (interleaved) instead of after each 4-MFMA group
# speedup vs baseline: 1.0077x; 1.0062x over previous
; #define SBAR() __builtin_amdgcn_sched_barrier(0)
; #define VF_WAIT(N) do { asm volatile("s_waitcnt lgkmcnt(" #N ")" ::: "memory"); SBAR(); } while (0)
; #define A_WAITBAR(N) asm volatile("s_waitcnt vmcnt(" #N ") lgkmcnt(0) ; A256BAR\n\ts_barrier" ::: "memory")
; #define DMA_V(t, sl) do { const char* b_ = Vb + (size_t)(t) * TSTRIDE; const unsigned d_ = RFL(vdst + (sl) * 32768); glds16(b_ + voff[0], d_); glds16(b_ + voff[1], d_ + 1024); glds16(b_ + voff[2], d_ + 2048); glds16(b_ + voff[3], d_ + 3072); } while (0)
; __device__ __forceinline__ void pv8(f32x16* o, int vb, bf16x8 pa0, bf16x8 pa1, bf16x8 pa2, bf16x8 pa3) {
;   VFrag fa, fb; const int vb2 = vb + 16384;
;   vf_read<0>(fa, vb);
;   vf_read<1>(fb, vb);  VF_WAIT(8); vf_mma(o[0], fa, pa0, pa1, pa2, pa3); SBAR();
;   vf_read<2>(fa, vb);  VF_WAIT(8); vf_mma(o[1], fb, pa0, pa1, pa2, pa3); SBAR();
;   vf_read<3>(fb, vb);  VF_WAIT(8); vf_mma(o[2], fa, pa0, pa1, pa2, pa3); SBAR();
;   vf_read<0>(fa, vb2); VF_WAIT(8); vf_mma(o[3], fb, pa0, pa1, pa2, pa3); SBAR();
;   vf_read<1>(fb, vb2); VF_WAIT(8); vf_mma(o[4], fa, pa0, pa1, pa2, pa3); SBAR();
;   vf_read<2>(fa, vb2); VF_WAIT(8); vf_mma(o[5], fb, pa0, pa1, pa2, pa3); SBAR();
;   vf_read<3>(fb, vb2); VF_WAIT(8); vf_mma(o[6], fa, pa0, pa1, pa2, pa3); SBAR();
;   VF_WAIT(0); vf_mma(o[7], fb, pa0, pa1, pa2, pa3);
; }
; template <int mode> ...
;     ...
;     if (more) A_WAITBAR(6); else A_WAITBAR(0);
;     if (more) DMA_V(j + 2, s2);
;     pv8(o, vb0 + s0 * 32768, pa0, pa1, pa2, pa3);
;     if (more) A_WAITBAR(6); else A_WAITBAR(0);
.LBB0_363:
	v_lshl_add_u32 v220, s11, 15, v223
	ds_read_b64_tr_b16 v[144:145], v220 offset:0
	ds_read_b64_tr_b16 v[146:147], v220 offset:0x800
	ds_read_b64_tr_b16 v[148:149], v220 offset:0x1000
	ds_read_b64_tr_b16 v[150:151], v220 offset:0x1800
	ds_read_b64_tr_b16 v[152:153], v220 offset:0x2000
	ds_read_b64_tr_b16 v[154:155], v220 offset:0x2800
	ds_read_b64_tr_b16 v[156:157], v220 offset:0x3000
	ds_read_b64_tr_b16 v[158:159], v220 offset:0x3800
	ds_read_b64_tr_b16 v[194:195], v220 offset:0x200
	ds_read_b64_tr_b16 v[196:197], v220 offset:0xa00
	ds_read_b64_tr_b16 v[214:215], v220 offset:0x1200
	ds_read_b64_tr_b16 v[216:217], v220 offset:0x1a00
	ds_read_b64_tr_b16 v[228:229], v220 offset:0x2200
	ds_read_b64_tr_b16 v[230:231], v220 offset:0x2a00
	ds_read_b64_tr_b16 v[232:233], v220 offset:0x3200
	ds_read_b64_tr_b16 v[234:235], v220 offset:0x3a00
	s_waitcnt lgkmcnt(8)
	v_add_u32_e32 v221, 0x4000, v220
	v_mfma_f32_32x32x16_bf16 v[112:127], v[128:131], v[144:147], v[112:127]
	ds_read_b64_tr_b16 v[144:145], v220 offset:0x400
	ds_read_b64_tr_b16 v[146:147], v220 offset:0xc00
	v_mfma_f32_32x32x16_bf16 v[112:127], v[132:135], v[148:151], v[112:127]
	ds_read_b64_tr_b16 v[148:149], v220 offset:0x1400
	ds_read_b64_tr_b16 v[150:151], v220 offset:0x1c00
	v_mfma_f32_32x32x16_bf16 v[112:127], v[136:139], v[152:155], v[112:127]
	ds_read_b64_tr_b16 v[152:153], v220 offset:0x2400
	ds_read_b64_tr_b16 v[154:155], v220 offset:0x2c00
	v_mfma_f32_32x32x16_bf16 v[112:127], v[140:143], v[156:159], v[112:127]
	ds_read_b64_tr_b16 v[156:157], v220 offset:0x3400
	ds_read_b64_tr_b16 v[158:159], v220 offset:0x3c00
	s_waitcnt lgkmcnt(8)
	v_mfma_f32_32x32x16_bf16 v[96:111], v[128:131], v[194:197], v[96:111]
	ds_read_b64_tr_b16 v[194:195], v220 offset:0x600
	ds_read_b64_tr_b16 v[196:197], v220 offset:0xe00
	v_mfma_f32_32x32x16_bf16 v[96:111], v[132:135], v[214:217], v[96:111]
	ds_read_b64_tr_b16 v[214:215], v220 offset:0x1600
	ds_read_b64_tr_b16 v[216:217], v220 offset:0x1e00
	v_mfma_f32_32x32x16_bf16 v[96:111], v[136:139], v[228:231], v[96:111]
	ds_read_b64_tr_b16 v[228:229], v220 offset:0x2600
	ds_read_b64_tr_b16 v[230:231], v220 offset:0x2e00
	v_mfma_f32_32x32x16_bf16 v[96:111], v[140:143], v[232:235], v[96:111]
	ds_read_b64_tr_b16 v[232:233], v220 offset:0x3600
	ds_read_b64_tr_b16 v[234:235], v220 offset:0x3e00
	s_cbranch_vccnz .Lp0_nodma
	s_lshl_b32 s12, s9, 15
	s_add_i32 s12, s12, s7
	s_mov_b32 s13, m0
	s_mov_b32 m0, s12
	s_nop 0
	global_load_lds_dwordx4 v204, s[38:39]
	s_add_i32 s24, s12, 0x400
	s_mov_b32 m0, s24
	s_nop 0
	global_load_lds_dwordx4 v206, s[38:39]
	s_add_i32 s24, s12, 0x800
	s_mov_b32 m0, s24
	s_nop 0
	global_load_lds_dwordx4 v208, s[38:39]
	s_add_i32 s24, s12, 0xc00
	s_mov_b32 m0, s24
	s_nop 0
	global_load_lds_dwordx4 v210, s[38:39]
	s_mov_b32 m0, s13
.Lp0_nodma:
	s_waitcnt lgkmcnt(8)
	v_mfma_f32_32x32x16_bf16 v[80:95], v[128:131], v[144:147], v[80:95]
	ds_read_b64_tr_b16 v[144:145], v221 offset:0
	ds_read_b64_tr_b16 v[146:147], v221 offset:0x800
	v_mfma_f32_32x32x16_bf16 v[80:95], v[132:135], v[148:151], v[80:95]
	ds_read_b64_tr_b16 v[148:149], v221 offset:0x1000
	ds_read_b64_tr_b16 v[150:151], v221 offset:0x1800
	v_mfma_f32_32x32x16_bf16 v[80:95], v[136:139], v[152:155], v[80:95]
	ds_read_b64_tr_b16 v[152:153], v221 offset:0x2000
	ds_read_b64_tr_b16 v[154:155], v221 offset:0x2800
	v_mfma_f32_32x32x16_bf16 v[80:95], v[140:143], v[156:159], v[80:95]
	ds_read_b64_tr_b16 v[156:157], v221 offset:0x3000
	ds_read_b64_tr_b16 v[158:159], v221 offset:0x3800
	s_waitcnt lgkmcnt(8)
	v_mfma_f32_32x32x16_bf16 v[64:79], v[128:131], v[194:197], v[64:79]
	ds_read_b64_tr_b16 v[194:195], v221 offset:0x200
	ds_read_b64_tr_b16 v[196:197], v221 offset:0xa00
	v_mfma_f32_32x32x16_bf16 v[64:79], v[132:135], v[214:217], v[64:79]
	ds_read_b64_tr_b16 v[214:215], v221 offset:0x1200
	ds_read_b64_tr_b16 v[216:217], v221 offset:0x1a00
	v_mfma_f32_32x32x16_bf16 v[64:79], v[136:139], v[228:231], v[64:79]
	ds_read_b64_tr_b16 v[228:229], v221 offset:0x2200
	ds_read_b64_tr_b16 v[230:231], v221 offset:0x2a00
	v_mfma_f32_32x32x16_bf16 v[64:79], v[140:143], v[232:235], v[64:79]
	ds_read_b64_tr_b16 v[232:233], v221 offset:0x3200
	ds_read_b64_tr_b16 v[234:235], v221 offset:0x3a00
	s_waitcnt lgkmcnt(8)
	v_mfma_f32_32x32x16_bf16 v[48:63], v[128:131], v[144:147], v[48:63]
	ds_read_b64_tr_b16 v[144:145], v221 offset:0x400
	ds_read_b64_tr_b16 v[146:147], v221 offset:0xc00
	v_mfma_f32_32x32x16_bf16 v[48:63], v[132:135], v[148:151], v[48:63]
	ds_read_b64_tr_b16 v[148:149], v221 offset:0x1400
	ds_read_b64_tr_b16 v[150:151], v221 offset:0x1c00
	v_mfma_f32_32x32x16_bf16 v[48:63], v[136:139], v[152:155], v[48:63]
	ds_read_b64_tr_b16 v[152:153], v221 offset:0x2400
	ds_read_b64_tr_b16 v[154:155], v221 offset:0x2c00
	v_mfma_f32_32x32x16_bf16 v[48:63], v[140:143], v[156:159], v[48:63]
	ds_read_b64_tr_b16 v[156:157], v221 offset:0x3400
	ds_read_b64_tr_b16 v[158:159], v221 offset:0x3c00
	s_waitcnt lgkmcnt(8)
	v_mfma_f32_32x32x16_bf16 v[32:47], v[128:131], v[194:197], v[32:47]
	ds_read_b64_tr_b16 v[194:195], v221 offset:0x600
	ds_read_b64_tr_b16 v[196:197], v221 offset:0xe00
	v_mfma_f32_32x32x16_bf16 v[32:47], v[132:135], v[214:217], v[32:47]
	ds_read_b64_tr_b16 v[214:215], v221 offset:0x1600
	ds_read_b64_tr_b16 v[216:217], v221 offset:0x1e00
	v_mfma_f32_32x32x16_bf16 v[32:47], v[136:139], v[228:231], v[32:47]
	ds_read_b64_tr_b16 v[228:229], v221 offset:0x2600
	ds_read_b64_tr_b16 v[230:231], v221 offset:0x2e00
	v_mfma_f32_32x32x16_bf16 v[32:47], v[140:143], v[232:235], v[32:47]
	ds_read_b64_tr_b16 v[232:233], v221 offset:0x3600
	ds_read_b64_tr_b16 v[234:235], v221 offset:0x3e00
	s_waitcnt lgkmcnt(8)
	v_mfma_f32_32x32x16_bf16 v[16:31], v[128:131], v[144:147], v[16:31]
	v_mfma_f32_32x32x16_bf16 v[16:31], v[132:135], v[148:151], v[16:31]
	v_mfma_f32_32x32x16_bf16 v[16:31], v[136:139], v[152:155], v[16:31]
	v_mfma_f32_32x32x16_bf16 v[16:31], v[140:143], v[156:159], v[16:31]
	s_waitcnt lgkmcnt(0)
	v_mfma_f32_32x32x16_bf16 v[0:15], v[128:131], v[194:197], v[0:15]
	s_and_b64 vcc, exec, s[90:91]
	v_mfma_f32_32x32x16_bf16 v[0:15], v[132:135], v[214:217], v[0:15]
	v_mfma_f32_32x32x16_bf16 v[0:15], v[136:139], v[228:231], v[0:15]
	v_mfma_f32_32x32x16_bf16 v[0:15], v[140:143], v[232:235], v[0:15]
	s_cbranch_vccnz .Lm0_ybar0
	s_waitcnt vmcnt(6) lgkmcnt(0)
	s_barrier

; #define SBAR() __builtin_amdgcn_sched_barrier(0)
; #define VF_WAIT(N) do { asm volatile("s_waitcnt lgkmcnt(" #N ")" ::: "memory"); SBAR(); } while (0)
; #define A_WAITBAR(N) asm volatile("s_waitcnt vmcnt(" #N ") lgkmcnt(0) ; A256BAR\n\ts_barrier" ::: "memory")
; #define DMA_V(t, sl) do { const char* b_ = Vb + (size_t)(t) * TSTRIDE; const unsigned d_ = RFL(vdst + (sl) * 32768); glds16(b_ + voff[0], d_); glds16(b_ + voff[1], d_ + 1024); glds16(b_ + voff[2], d_ + 2048); glds16(b_ + voff[3], d_ + 3072); } while (0)
; __device__ __forceinline__ void pv8(f32x16* o, int vb, bf16x8 pa0, bf16x8 pa1, bf16x8 pa2, bf16x8 pa3) {
;   VFrag fa, fb; const int vb2 = vb + 16384;
;   vf_read<0>(fa, vb);
;   vf_read<1>(fb, vb);  VF_WAIT(8); vf_mma(o[0], fa, pa0, pa1, pa2, pa3); SBAR();
;   vf_read<2>(fa, vb);  VF_WAIT(8); vf_mma(o[1], fb, pa0, pa1, pa2, pa3); SBAR();
;   vf_read<3>(fb, vb);  VF_WAIT(8); vf_mma(o[2], fa, pa0, pa1, pa2, pa3); SBAR();
;   vf_read<0>(fa, vb2); VF_WAIT(8); vf_mma(o[3], fb, pa0, pa1, pa2, pa3); SBAR();
;   vf_read<1>(fb, vb2); VF_WAIT(8); vf_mma(o[4], fa, pa0, pa1, pa2, pa3); SBAR();
;   vf_read<2>(fa, vb2); VF_WAIT(8); vf_mma(o[5], fb, pa0, pa1, pa2, pa3); SBAR();
;   vf_read<3>(fb, vb2); VF_WAIT(8); vf_mma(o[6], fa, pa0, pa1, pa2, pa3); SBAR();
;   VF_WAIT(0); vf_mma(o[7], fb, pa0, pa1, pa2, pa3);
; }
; template <int mode> ...
;     ...
;     if (more) A_WAITBAR(6); else A_WAITBAR(0);
;     if (more) DMA_V(j + 2, s2);
;     pv8(o, vb0 + s0 * 32768, pa0, pa1, pa2, pa3);
;     if (more) A_WAITBAR(6); else A_WAITBAR(0);
.LBB0_396:
	v_lshl_add_u32 v231, s10, 15, v226
	ds_read_b64_tr_b16 v[144:145], v231 offset:0
	ds_read_b64_tr_b16 v[146:147], v231 offset:0x800
	ds_read_b64_tr_b16 v[148:149], v231 offset:0x1000
	ds_read_b64_tr_b16 v[150:151], v231 offset:0x1800
	ds_read_b64_tr_b16 v[152:153], v231 offset:0x2000
	ds_read_b64_tr_b16 v[154:155], v231 offset:0x2800
	ds_read_b64_tr_b16 v[156:157], v231 offset:0x3000
	ds_read_b64_tr_b16 v[158:159], v231 offset:0x3800
	ds_read_b64_tr_b16 v[194:195], v231 offset:0x200
	ds_read_b64_tr_b16 v[196:197], v231 offset:0xa00
	ds_read_b64_tr_b16 v[214:215], v231 offset:0x1200
	ds_read_b64_tr_b16 v[216:217], v231 offset:0x1a00
	ds_read_b64_tr_b16 v[220:221], v231 offset:0x2200
	ds_read_b64_tr_b16 v[222:223], v231 offset:0x2a00
	ds_read_b64_tr_b16 v[232:233], v231 offset:0x3200
	ds_read_b64_tr_b16 v[234:235], v231 offset:0x3a00
	s_waitcnt lgkmcnt(8)
	v_add_u32_e32 v236, 0x4000, v231
	v_mfma_f32_32x32x16_bf16 v[16:31], v[128:131], v[144:147], v[16:31]
	ds_read_b64_tr_b16 v[144:145], v231 offset:0x400
	ds_read_b64_tr_b16 v[146:147], v231 offset:0xc00
	v_mfma_f32_32x32x16_bf16 v[16:31], v[132:135], v[148:151], v[16:31]
	ds_read_b64_tr_b16 v[148:149], v231 offset:0x1400
	ds_read_b64_tr_b16 v[150:151], v231 offset:0x1c00
	v_mfma_f32_32x32x16_bf16 v[16:31], v[136:139], v[152:155], v[16:31]
	ds_read_b64_tr_b16 v[152:153], v231 offset:0x2400
	ds_read_b64_tr_b16 v[154:155], v231 offset:0x2c00
	v_mfma_f32_32x32x16_bf16 v[16:31], v[140:143], v[156:159], v[16:31]
	ds_read_b64_tr_b16 v[156:157], v231 offset:0x3400
	ds_read_b64_tr_b16 v[158:159], v231 offset:0x3c00
	s_waitcnt lgkmcnt(8)
	v_mfma_f32_32x32x16_bf16 v[32:47], v[128:131], v[194:197], v[32:47]
	ds_read_b64_tr_b16 v[194:195], v231 offset:0x600
	ds_read_b64_tr_b16 v[196:197], v231 offset:0xe00
	v_mfma_f32_32x32x16_bf16 v[32:47], v[132:135], v[214:217], v[32:47]
	ds_read_b64_tr_b16 v[214:215], v231 offset:0x1600
	ds_read_b64_tr_b16 v[216:217], v231 offset:0x1e00
	v_mfma_f32_32x32x16_bf16 v[32:47], v[136:139], v[220:223], v[32:47]
	ds_read_b64_tr_b16 v[220:221], v231 offset:0x2600
	ds_read_b64_tr_b16 v[222:223], v231 offset:0x2e00
	v_mfma_f32_32x32x16_bf16 v[32:47], v[140:143], v[232:235], v[32:47]
	ds_read_b64_tr_b16 v[232:233], v231 offset:0x3600
	ds_read_b64_tr_b16 v[234:235], v231 offset:0x3e00
	s_cbranch_vccnz .Lp1_nodma
	s_lshl_b32 s11, s7, 15
	s_add_i32 s11, s11, s5
	s_mov_b32 s12, m0
	s_mov_b32 m0, s11
	s_nop 0
	global_load_lds_dwordx4 v204, s[60:61]
	s_add_i32 s13, s11, 0x400
	s_mov_b32 m0, s13
	s_nop 0
	global_load_lds_dwordx4 v206, s[60:61]
	s_add_i32 s13, s11, 0x800
	s_mov_b32 m0, s13
	s_nop 0
	global_load_lds_dwordx4 v208, s[60:61]
	s_add_i32 s13, s11, 0xc00
	s_mov_b32 m0, s13
	s_nop 0
	global_load_lds_dwordx4 v210, s[60:61]
	s_mov_b32 m0, s12
.Lp1_nodma:
	s_waitcnt lgkmcnt(8)
	v_mfma_f32_32x32x16_bf16 v[96:111], v[128:131], v[144:147], v[96:111]
	ds_read_b64_tr_b16 v[144:145], v236 offset:0
	ds_read_b64_tr_b16 v[146:147], v236 offset:0x800
	v_mfma_f32_32x32x16_bf16 v[96:111], v[132:135], v[148:151], v[96:111]
	ds_read_b64_tr_b16 v[148:149], v236 offset:0x1000
	ds_read_b64_tr_b16 v[150:151], v236 offset:0x1800
	v_mfma_f32_32x32x16_bf16 v[96:111], v[136:139], v[152:155], v[96:111]
	ds_read_b64_tr_b16 v[152:153], v236 offset:0x2000
	ds_read_b64_tr_b16 v[154:155], v236 offset:0x2800
	v_mfma_f32_32x32x16_bf16 v[96:111], v[140:143], v[156:159], v[96:111]
	ds_read_b64_tr_b16 v[156:157], v236 offset:0x3000
	ds_read_b64_tr_b16 v[158:159], v236 offset:0x3800
	s_waitcnt lgkmcnt(8)
	v_mfma_f32_32x32x16_bf16 v[112:127], v[128:131], v[194:197], v[112:127]
	ds_read_b64_tr_b16 v[194:195], v236 offset:0x200
	ds_read_b64_tr_b16 v[196:197], v236 offset:0xa00
	v_mfma_f32_32x32x16_bf16 v[112:127], v[132:135], v[214:217], v[112:127]
	ds_read_b64_tr_b16 v[214:215], v236 offset:0x1200
	ds_read_b64_tr_b16 v[216:217], v236 offset:0x1a00
	v_mfma_f32_32x32x16_bf16 v[112:127], v[136:139], v[220:223], v[112:127]
	ds_read_b64_tr_b16 v[220:221], v236 offset:0x2200
	ds_read_b64_tr_b16 v[222:223], v236 offset:0x2a00
	v_mfma_f32_32x32x16_bf16 v[112:127], v[140:143], v[232:235], v[112:127]
	ds_read_b64_tr_b16 v[232:233], v236 offset:0x3200
	ds_read_b64_tr_b16 v[234:235], v236 offset:0x3a00
	s_waitcnt lgkmcnt(8)
	v_mfma_f32_32x32x16_bf16 v[64:79], v[128:131], v[144:147], v[64:79]
	ds_read_b64_tr_b16 v[144:145], v236 offset:0x400
	ds_read_b64_tr_b16 v[146:147], v236 offset:0xc00
	v_mfma_f32_32x32x16_bf16 v[64:79], v[132:135], v[148:151], v[64:79]
	ds_read_b64_tr_b16 v[148:149], v236 offset:0x1400
	ds_read_b64_tr_b16 v[150:151], v236 offset:0x1c00
	v_mfma_f32_32x32x16_bf16 v[64:79], v[136:139], v[152:155], v[64:79]
	ds_read_b64_tr_b16 v[152:153], v236 offset:0x2400
	ds_read_b64_tr_b16 v[154:155], v236 offset:0x2c00
	v_mfma_f32_32x32x16_bf16 v[64:79], v[140:143], v[156:159], v[64:79]
	ds_read_b64_tr_b16 v[156:157], v236 offset:0x3400
	ds_read_b64_tr_b16 v[158:159], v236 offset:0x3c00
	s_waitcnt lgkmcnt(8)
	v_mfma_f32_32x32x16_bf16 v[48:63], v[128:131], v[194:197], v[48:63]
	ds_read_b64_tr_b16 v[194:195], v236 offset:0x600
	ds_read_b64_tr_b16 v[196:197], v236 offset:0xe00
	v_mfma_f32_32x32x16_bf16 v[48:63], v[132:135], v[214:217], v[48:63]
	ds_read_b64_tr_b16 v[214:215], v236 offset:0x1600
	ds_read_b64_tr_b16 v[216:217], v236 offset:0x1e00
	v_mfma_f32_32x32x16_bf16 v[48:63], v[136:139], v[220:223], v[48:63]
	ds_read_b64_tr_b16 v[220:221], v236 offset:0x2600
	ds_read_b64_tr_b16 v[222:223], v236 offset:0x2e00
	v_mfma_f32_32x32x16_bf16 v[48:63], v[140:143], v[232:235], v[48:63]
	ds_read_b64_tr_b16 v[232:233], v236 offset:0x3600
	ds_read_b64_tr_b16 v[234:235], v236 offset:0x3e00
	s_waitcnt lgkmcnt(8)
	v_mfma_f32_32x32x16_bf16 v[0:15], v[128:131], v[144:147], v[0:15]
	v_mfma_f32_32x32x16_bf16 v[0:15], v[132:135], v[148:151], v[0:15]
	v_mfma_f32_32x32x16_bf16 v[0:15], v[136:139], v[152:155], v[0:15]
	v_mfma_f32_32x32x16_bf16 v[0:15], v[140:143], v[156:159], v[0:15]
	s_waitcnt lgkmcnt(0)
	v_mfma_f32_32x32x16_bf16 v[80:95], v[128:131], v[194:197], v[80:95]
	s_and_b64 vcc, exec, s[50:51]
	v_mfma_f32_32x32x16_bf16 v[80:95], v[132:135], v[214:217], v[80:95]
	v_mfma_f32_32x32x16_bf16 v[80:95], v[136:139], v[220:223], v[80:95]
	v_mfma_f32_32x32x16_bf16 v[80:95], v[140:143], v[232:235], v[80:95]
	s_cbranch_vccnz .Lm1_ybar0
	s_waitcnt vmcnt(6) lgkmcnt(0)
	s_barrier
